# GEMM residual epilogue: 32 serialized float4 read-modify-writes replaced by two batches of 16 loads in flight with counted waits
# speedup vs baseline: 1.0072x; 1.0072x over previous
;     __device__ __forceinline__ void operator()(const f32x4 (&acc)[2][2][4][2], const Unit& u, int wr, int wc, int fr, int fq) const {
;         const int row0 = u.pm * BM + wr * 64 + fr; const int col0 = u.pn * BM + wc * 32 + 4 * fq;
; #pragma unroll
;         for (int ai = 0; ai < 2; ++ai)
; #pragma unroll
;             for (int m = 0; m < 4; ++m) { float* rowp = out + (size_t)(row0 + ai * HALF + m * 16) * ldc + col0;
; #pragma unroll
;                 for (int bj = 0; bj < 2; ++bj)
; #pragma unroll
;                     for (int n = 0; n < 2; ++n) { f32x4* q = (f32x4*)(rowp + bj * HALF + n * 16); *q = *q + acc[ai][bj][m][n]; }
;                 asm volatile("" ::: "memory"); }
.LBB0_48:
	v_lshl_add_u32 v140, s46, 8, v1
	v_lshl_or_b32 v138, s85, 8, v150
	v_ashrrev_i32_e32 v141, 31, v140
	v_ashrrev_i32_e32 v139, 31, v138
	v_lshlrev_b64 v[142:143], 12, v[140:141]
	v_lshl_add_u64 v[184:185], s[66:67], 0, v[142:143]
	v_lshlrev_b64 v[142:143], 2, v[138:139]
	v_lshl_add_u64 v[138:139], v[184:185], 0, v[142:143]
	s_mov_b32 s62, 0xc000
	s_mov_b32 s63, 0x12000
	s_mov_b32 s86, 0x30000
	s_mov_b64 s[2:3], 0x10000
	v_lshl_add_u64 v[140:141], v[138:139], 0, s[2:3]
	s_mov_b64 s[2:3], 0x20000
	v_lshl_add_u64 v[142:143], v[138:139], 0, s[2:3]
	s_mov_b64 s[2:3], 0x30000
	v_lshl_add_u64 v[196:197], v[138:139], 0, s[2:3]
	global_load_dwordx4 v[184:187], v[138:139], off
	global_load_dwordx4 v[188:191], v[138:139], off offset:64
	global_load_dwordx4 v[192:195], v[138:139], off offset:512
	global_load_dwordx4 v[200:203], v[138:139], off offset:576
	global_load_dwordx4 v[204:207], v[140:141], off
	global_load_dwordx4 v[208:211], v[140:141], off offset:64
	global_load_dwordx4 v[212:215], v[140:141], off offset:512
	global_load_dwordx4 v[216:219], v[140:141], off offset:576
	global_load_dwordx4 v[220:223], v[142:143], off
	global_load_dwordx4 v[224:227], v[142:143], off offset:64
	global_load_dwordx4 v[228:231], v[142:143], off offset:512
	global_load_dwordx4 v[232:235], v[142:143], off offset:576
	global_load_dwordx4 v[236:239], v[196:197], off
	global_load_dwordx4 v[240:243], v[196:197], off offset:64
	global_load_dwordx4 v[244:247], v[196:197], off offset:512
	global_load_dwordx4 v[248:251], v[196:197], off offset:576
	s_waitcnt vmcnt(15)
	v_pk_add_f32 v[128:129], v[128:129], v[186:187]
	v_pk_add_f32 v[126:127], v[126:127], v[184:185]
	global_store_dwordx4 v[138:139], v[126:129], off
	s_waitcnt vmcnt(15)
	v_pk_add_f32 v[124:125], v[124:125], v[190:191]
	v_pk_add_f32 v[122:123], v[122:123], v[188:189]
	global_store_dwordx4 v[138:139], v[122:125], off offset:64
	s_waitcnt vmcnt(15)
	v_pk_add_f32 v[120:121], v[120:121], v[194:195]
	v_pk_add_f32 v[118:119], v[118:119], v[192:193]
	global_store_dwordx4 v[138:139], v[118:121], off offset:512
	s_waitcnt vmcnt(15)
	v_pk_add_f32 v[116:117], v[116:117], v[202:203]
	v_pk_add_f32 v[114:115], v[114:115], v[200:201]
	global_store_dwordx4 v[138:139], v[114:117], off offset:576
	s_waitcnt vmcnt(15)
	v_pk_add_f32 v[112:113], v[112:113], v[206:207]
	v_pk_add_f32 v[110:111], v[110:111], v[204:205]
	global_store_dwordx4 v[140:141], v[110:113], off
	s_waitcnt vmcnt(15)
	v_pk_add_f32 v[108:109], v[108:109], v[210:211]
	v_pk_add_f32 v[106:107], v[106:107], v[208:209]
	global_store_dwordx4 v[140:141], v[106:109], off offset:64
	s_waitcnt vmcnt(15)
	v_pk_add_f32 v[104:105], v[104:105], v[214:215]
	v_pk_add_f32 v[102:103], v[102:103], v[212:213]
	global_store_dwordx4 v[140:141], v[102:105], off offset:512
	s_waitcnt vmcnt(15)
	v_pk_add_f32 v[100:101], v[100:101], v[218:219]
	v_pk_add_f32 v[98:99], v[98:99], v[216:217]
	global_store_dwordx4 v[140:141], v[98:101], off offset:576
	s_waitcnt vmcnt(15)
	v_pk_add_f32 v[96:97], v[96:97], v[222:223]
	v_pk_add_f32 v[94:95], v[94:95], v[220:221]
	global_store_dwordx4 v[142:143], v[94:97], off
	s_waitcnt vmcnt(15)
	v_pk_add_f32 v[92:93], v[92:93], v[226:227]
	v_pk_add_f32 v[90:91], v[90:91], v[224:225]
	global_store_dwordx4 v[142:143], v[90:93], off offset:64
	s_waitcnt vmcnt(15)
	v_pk_add_f32 v[88:89], v[88:89], v[230:231]
	v_pk_add_f32 v[86:87], v[86:87], v[228:229]
	global_store_dwordx4 v[142:143], v[86:89], off offset:512
	s_waitcnt vmcnt(15)
	v_pk_add_f32 v[84:85], v[84:85], v[234:235]
	v_pk_add_f32 v[82:83], v[82:83], v[232:233]
	global_store_dwordx4 v[142:143], v[82:85], off offset:576
	s_waitcnt vmcnt(15)
	v_pk_add_f32 v[80:81], v[80:81], v[238:239]
	v_pk_add_f32 v[78:79], v[78:79], v[236:237]
	global_store_dwordx4 v[196:197], v[78:81], off
	s_waitcnt vmcnt(15)
	v_pk_add_f32 v[76:77], v[76:77], v[242:243]
	v_pk_add_f32 v[74:75], v[74:75], v[240:241]
	global_store_dwordx4 v[196:197], v[74:77], off offset:64
	s_waitcnt vmcnt(15)
	v_pk_add_f32 v[72:73], v[72:73], v[246:247]
	v_pk_add_f32 v[70:71], v[70:71], v[244:245]
	global_store_dwordx4 v[196:197], v[70:73], off offset:512
	s_waitcnt vmcnt(15)
;     __device__ __forceinline__ void operator()(const f32x4 (&acc)[2][2][4][2], const Unit& u, int wr, int wc, int fr, int fq) const {
;         const int row0 = u.pm * BM + wr * 64 + fr; const int col0 = u.pn * BM + wc * 32 + 4 * fq;
; #pragma unroll
;         for (int ai = 0; ai < 2; ++ai)
; #pragma unroll
;             for (int m = 0; m < 4; ++m) { float* rowp = out + (size_t)(row0 + ai * HALF + m * 16) * ldc + col0;
; #pragma unroll
;                 for (int bj = 0; bj < 2; ++bj)
; #pragma unroll
;                     for (int n = 0; n < 2; ++n) { f32x4* q = (f32x4*)(rowp + bj * HALF + n * 16); *q = *q + acc[ai][bj][m][n]; }
;                 asm volatile("" ::: "memory"); }
	v_pk_add_f32 v[68:69], v[68:69], v[250:251]
	v_pk_add_f32 v[66:67], v[66:67], v[248:249]
	global_store_dwordx4 v[196:197], v[66:69], off offset:576
	s_nop 1
	s_mov_b64 s[2:3], 0x80000
	v_lshl_add_u64 v[252:253], v[138:139], 0, s[2:3]
	s_mov_b64 s[2:3], 0x90000
	v_lshl_add_u64 v[140:141], v[138:139], 0, s[2:3]
	s_mov_b64 s[2:3], 0xa0000
	v_lshl_add_u64 v[142:143], v[138:139], 0, s[2:3]
	s_mov_b64 s[2:3], 0xb0000
	v_lshl_add_u64 v[196:197], v[138:139], 0, s[2:3]
	global_load_dwordx4 v[184:187], v[252:253], off
	global_load_dwordx4 v[188:191], v[252:253], off offset:64
	global_load_dwordx4 v[192:195], v[252:253], off offset:512
	global_load_dwordx4 v[200:203], v[252:253], off offset:576
	global_load_dwordx4 v[204:207], v[140:141], off
	global_load_dwordx4 v[208:211], v[140:141], off offset:64
	global_load_dwordx4 v[212:215], v[140:141], off offset:512
	global_load_dwordx4 v[216:219], v[140:141], off offset:576
	global_load_dwordx4 v[220:223], v[142:143], off
	global_load_dwordx4 v[224:227], v[142:143], off offset:64
	global_load_dwordx4 v[228:231], v[142:143], off offset:512
	global_load_dwordx4 v[232:235], v[142:143], off offset:576
	global_load_dwordx4 v[236:239], v[196:197], off
	global_load_dwordx4 v[240:243], v[196:197], off offset:64
	global_load_dwordx4 v[244:247], v[196:197], off offset:512
	global_load_dwordx4 v[248:251], v[196:197], off offset:576
	s_waitcnt vmcnt(15)
	v_pk_add_f32 v[64:65], v[64:65], v[186:187]
	v_pk_add_f32 v[62:63], v[62:63], v[184:185]
	global_store_dwordx4 v[252:253], v[62:65], off
	s_waitcnt vmcnt(15)
	v_pk_add_f32 v[60:61], v[60:61], v[190:191]
	v_pk_add_f32 v[58:59], v[58:59], v[188:189]
	global_store_dwordx4 v[252:253], v[58:61], off offset:64
	s_waitcnt vmcnt(15)
	v_pk_add_f32 v[56:57], v[56:57], v[194:195]
	v_pk_add_f32 v[54:55], v[54:55], v[192:193]
	global_store_dwordx4 v[252:253], v[54:57], off offset:512
	s_waitcnt vmcnt(15)
	v_pk_add_f32 v[52:53], v[52:53], v[202:203]
	v_pk_add_f32 v[50:51], v[50:51], v[200:201]
	global_store_dwordx4 v[252:253], v[50:53], off offset:576
	s_waitcnt vmcnt(15)
	v_pk_add_f32 v[48:49], v[48:49], v[206:207]
	v_pk_add_f32 v[46:47], v[46:47], v[204:205]
	global_store_dwordx4 v[140:141], v[46:49], off
	s_waitcnt vmcnt(15)
	v_pk_add_f32 v[44:45], v[44:45], v[210:211]
	v_pk_add_f32 v[42:43], v[42:43], v[208:209]
	global_store_dwordx4 v[140:141], v[42:45], off offset:64
	s_waitcnt vmcnt(15)
	v_pk_add_f32 v[40:41], v[40:41], v[214:215]
	v_pk_add_f32 v[38:39], v[38:39], v[212:213]
	global_store_dwordx4 v[140:141], v[38:41], off offset:512
	s_waitcnt vmcnt(15)
	v_pk_add_f32 v[36:37], v[36:37], v[218:219]
	v_pk_add_f32 v[34:35], v[34:35], v[216:217]
	global_store_dwordx4 v[140:141], v[34:37], off offset:576
	s_waitcnt vmcnt(15)
	v_pk_add_f32 v[32:33], v[32:33], v[222:223]
	v_pk_add_f32 v[30:31], v[30:31], v[220:221]
	global_store_dwordx4 v[142:143], v[30:33], off
	s_waitcnt vmcnt(15)
	v_pk_add_f32 v[28:29], v[28:29], v[226:227]
	v_pk_add_f32 v[26:27], v[26:27], v[224:225]
	global_store_dwordx4 v[142:143], v[26:29], off offset:64
	s_waitcnt vmcnt(15)
	v_pk_add_f32 v[24:25], v[24:25], v[230:231]
	v_pk_add_f32 v[22:23], v[22:23], v[228:229]
	global_store_dwordx4 v[142:143], v[22:25], off offset:512
	s_waitcnt vmcnt(15)
	v_pk_add_f32 v[20:21], v[20:21], v[234:235]
	v_pk_add_f32 v[18:19], v[18:19], v[232:233]
	global_store_dwordx4 v[142:143], v[18:21], off offset:576
	s_waitcnt vmcnt(15)
	v_pk_add_f32 v[16:17], v[16:17], v[238:239]
	v_pk_add_f32 v[14:15], v[14:15], v[236:237]
	global_store_dwordx4 v[196:197], v[14:17], off
	s_waitcnt vmcnt(15)
	v_pk_add_f32 v[12:13], v[12:13], v[242:243]
	v_pk_add_f32 v[10:11], v[10:11], v[240:241]
	global_store_dwordx4 v[196:197], v[10:13], off offset:64
	s_waitcnt vmcnt(15)
	v_pk_add_f32 v[8:9], v[8:9], v[246:247]
	v_pk_add_f32 v[6:7], v[6:7], v[244:245]
	global_store_dwordx4 v[196:197], v[6:9], off offset:512
	s_waitcnt vmcnt(15)
	v_pk_add_f32 v[4:5], v[4:5], v[250:251]
	v_pk_add_f32 v[2:3], v[2:3], v[248:249]
	global_store_dwordx4 v[196:197], v[2:5], off offset:576
	s_mov_b64 s[2:3], -1
	s_and_b64 vcc, exec, s[6:7]
	s_cbranch_vccnz .LBB0_33
	s_andn2_b64 vcc, exec, s[12:13]
	s_cbranch_vccnz .LBB0_32
	s_barrier
	s_branch .LBB0_32

;     __device__ __forceinline__ void operator()(const f32x4 (&acc)[2][2][4][2], const Unit& u, int wr, int wc, int fr, int fq) const {
;         const int row0 = u.pm * BM + wr * 64 + fr; const int col0 = u.pn * BM + wc * 32 + 4 * fq;
; #pragma unroll
;         for (int ai = 0; ai < 2; ++ai)
; #pragma unroll
;             for (int m = 0; m < 4; ++m) { float* rowp = out + (size_t)(row0 + ai * HALF + m * 16) * ldc + col0;
; #pragma unroll
;                 for (int bj = 0; bj < 2; ++bj)
; #pragma unroll
;                     for (int n = 0; n < 2; ++n) { f32x4* q = (f32x4*)(rowp + bj * HALF + n * 16); *q = *q + acc[ai][bj][m][n]; }
;                 asm volatile("" ::: "memory"); }
.LBB0_887:
	v_lshl_add_u32 v140, s18, 8, v1
	v_lshl_or_b32 v138, s46, 8, v165
	v_ashrrev_i32_e32 v141, 31, v140
	v_ashrrev_i32_e32 v139, 31, v138
	v_lshlrev_b64 v[142:143], 12, v[140:141]
	v_lshl_add_u64 v[168:169], s[66:67], 0, v[142:143]
	v_lshlrev_b64 v[142:143], 2, v[138:139]
	v_lshl_add_u64 v[138:139], v[168:169], 0, v[142:143]
	s_mov_b32 s62, 0xc000
	s_mov_b32 s63, 0x12000
	s_mov_b32 s86, 0x30000
	s_mov_b64 s[2:3], 0x10000
	v_lshl_add_u64 v[140:141], v[138:139], 0, s[2:3]
	s_mov_b64 s[2:3], 0x20000
	v_lshl_add_u64 v[142:143], v[138:139], 0, s[2:3]
	s_mov_b64 s[2:3], 0x30000
	v_lshl_add_u64 v[196:197], v[138:139], 0, s[2:3]
	global_load_dwordx4 v[184:187], v[138:139], off
	global_load_dwordx4 v[188:191], v[138:139], off offset:64
	global_load_dwordx4 v[192:195], v[138:139], off offset:512
	global_load_dwordx4 v[200:203], v[138:139], off offset:576
	global_load_dwordx4 v[204:207], v[140:141], off
	global_load_dwordx4 v[208:211], v[140:141], off offset:64
	global_load_dwordx4 v[212:215], v[140:141], off offset:512
	global_load_dwordx4 v[216:219], v[140:141], off offset:576
	global_load_dwordx4 v[220:223], v[142:143], off
	global_load_dwordx4 v[224:227], v[142:143], off offset:64
	global_load_dwordx4 v[228:231], v[142:143], off offset:512
	global_load_dwordx4 v[232:235], v[142:143], off offset:576
	global_load_dwordx4 v[236:239], v[196:197], off
	global_load_dwordx4 v[240:243], v[196:197], off offset:64
	global_load_dwordx4 v[244:247], v[196:197], off offset:512
	global_load_dwordx4 v[248:251], v[196:197], off offset:576
	s_waitcnt vmcnt(15)
	v_pk_add_f32 v[128:129], v[128:129], v[186:187]
	v_pk_add_f32 v[126:127], v[126:127], v[184:185]
	global_store_dwordx4 v[138:139], v[126:129], off
	s_waitcnt vmcnt(15)
	v_pk_add_f32 v[124:125], v[124:125], v[190:191]
	v_pk_add_f32 v[122:123], v[122:123], v[188:189]
	global_store_dwordx4 v[138:139], v[122:125], off offset:64
	s_waitcnt vmcnt(15)
	v_pk_add_f32 v[120:121], v[120:121], v[194:195]
	v_pk_add_f32 v[118:119], v[118:119], v[192:193]
	global_store_dwordx4 v[138:139], v[118:121], off offset:512
	s_waitcnt vmcnt(15)
	v_pk_add_f32 v[116:117], v[116:117], v[202:203]
	v_pk_add_f32 v[114:115], v[114:115], v[200:201]
	global_store_dwordx4 v[138:139], v[114:117], off offset:576
	s_waitcnt vmcnt(15)
	v_pk_add_f32 v[112:113], v[112:113], v[206:207]
	v_pk_add_f32 v[110:111], v[110:111], v[204:205]
	global_store_dwordx4 v[140:141], v[110:113], off
	s_waitcnt vmcnt(15)
	v_pk_add_f32 v[108:109], v[108:109], v[210:211]
	v_pk_add_f32 v[106:107], v[106:107], v[208:209]
	global_store_dwordx4 v[140:141], v[106:109], off offset:64
	s_waitcnt vmcnt(15)
	v_pk_add_f32 v[104:105], v[104:105], v[214:215]
	v_pk_add_f32 v[102:103], v[102:103], v[212:213]
	global_store_dwordx4 v[140:141], v[102:105], off offset:512
	s_waitcnt vmcnt(15)
	v_pk_add_f32 v[100:101], v[100:101], v[218:219]
	v_pk_add_f32 v[98:99], v[98:99], v[216:217]
	global_store_dwordx4 v[140:141], v[98:101], off offset:576
	s_waitcnt vmcnt(15)
	v_pk_add_f32 v[96:97], v[96:97], v[222:223]
	v_pk_add_f32 v[94:95], v[94:95], v[220:221]
	global_store_dwordx4 v[142:143], v[94:97], off
	s_waitcnt vmcnt(15)
	v_pk_add_f32 v[92:93], v[92:93], v[226:227]
	v_pk_add_f32 v[90:91], v[90:91], v[224:225]
	global_store_dwordx4 v[142:143], v[90:93], off offset:64
	s_waitcnt vmcnt(15)
	v_pk_add_f32 v[88:89], v[88:89], v[230:231]
	v_pk_add_f32 v[86:87], v[86:87], v[228:229]
	global_store_dwordx4 v[142:143], v[86:89], off offset:512
	s_waitcnt vmcnt(15)
	v_pk_add_f32 v[84:85], v[84:85], v[234:235]
	v_pk_add_f32 v[82:83], v[82:83], v[232:233]
	global_store_dwordx4 v[142:143], v[82:85], off offset:576
	s_waitcnt vmcnt(15)
	v_pk_add_f32 v[80:81], v[80:81], v[238:239]
	v_pk_add_f32 v[78:79], v[78:79], v[236:237]
	global_store_dwordx4 v[196:197], v[78:81], off
	s_waitcnt vmcnt(15)
	v_pk_add_f32 v[76:77], v[76:77], v[242:243]
	v_pk_add_f32 v[74:75], v[74:75], v[240:241]
	global_store_dwordx4 v[196:197], v[74:77], off offset:64
	s_waitcnt vmcnt(15)
	v_pk_add_f32 v[72:73], v[72:73], v[246:247]
	v_pk_add_f32 v[70:71], v[70:71], v[244:245]
	global_store_dwordx4 v[196:197], v[70:73], off offset:512
	s_waitcnt vmcnt(15)
;     __device__ __forceinline__ void operator()(const f32x4 (&acc)[2][2][4][2], const Unit& u, int wr, int wc, int fr, int fq) const {
;         const int row0 = u.pm * BM + wr * 64 + fr; const int col0 = u.pn * BM + wc * 32 + 4 * fq;
; #pragma unroll
;         for (int ai = 0; ai < 2; ++ai)
; #pragma unroll
;             for (int m = 0; m < 4; ++m) { float* rowp = out + (size_t)(row0 + ai * HALF + m * 16) * ldc + col0;
; #pragma unroll
;                 for (int bj = 0; bj < 2; ++bj)
; #pragma unroll
;                     for (int n = 0; n < 2; ++n) { f32x4* q = (f32x4*)(rowp + bj * HALF + n * 16); *q = *q + acc[ai][bj][m][n]; }
;                 asm volatile("" ::: "memory"); }
	v_pk_add_f32 v[68:69], v[68:69], v[250:251]
	v_pk_add_f32 v[66:67], v[66:67], v[248:249]
	global_store_dwordx4 v[196:197], v[66:69], off offset:576
	s_nop 1
	s_mov_b64 s[2:3], 0x80000
	v_lshl_add_u64 v[252:253], v[138:139], 0, s[2:3]
	s_mov_b64 s[2:3], 0x90000
	v_lshl_add_u64 v[140:141], v[138:139], 0, s[2:3]
	s_mov_b64 s[2:3], 0xa0000
	v_lshl_add_u64 v[142:143], v[138:139], 0, s[2:3]
	s_mov_b64 s[2:3], 0xb0000
	v_lshl_add_u64 v[196:197], v[138:139], 0, s[2:3]
	global_load_dwordx4 v[184:187], v[252:253], off
	global_load_dwordx4 v[188:191], v[252:253], off offset:64
	global_load_dwordx4 v[192:195], v[252:253], off offset:512
	global_load_dwordx4 v[200:203], v[252:253], off offset:576
	global_load_dwordx4 v[204:207], v[140:141], off
	global_load_dwordx4 v[208:211], v[140:141], off offset:64
	global_load_dwordx4 v[212:215], v[140:141], off offset:512
	global_load_dwordx4 v[216:219], v[140:141], off offset:576
	global_load_dwordx4 v[220:223], v[142:143], off
	global_load_dwordx4 v[224:227], v[142:143], off offset:64
	global_load_dwordx4 v[228:231], v[142:143], off offset:512
	global_load_dwordx4 v[232:235], v[142:143], off offset:576
	global_load_dwordx4 v[236:239], v[196:197], off
	global_load_dwordx4 v[240:243], v[196:197], off offset:64
	global_load_dwordx4 v[244:247], v[196:197], off offset:512
	global_load_dwordx4 v[248:251], v[196:197], off offset:576
	s_waitcnt vmcnt(15)
	v_pk_add_f32 v[64:65], v[64:65], v[186:187]
	v_pk_add_f32 v[62:63], v[62:63], v[184:185]
	global_store_dwordx4 v[252:253], v[62:65], off
	s_waitcnt vmcnt(15)
	v_pk_add_f32 v[60:61], v[60:61], v[190:191]
	v_pk_add_f32 v[58:59], v[58:59], v[188:189]
	global_store_dwordx4 v[252:253], v[58:61], off offset:64
	s_waitcnt vmcnt(15)
	v_pk_add_f32 v[56:57], v[56:57], v[194:195]
	v_pk_add_f32 v[54:55], v[54:55], v[192:193]
	global_store_dwordx4 v[252:253], v[54:57], off offset:512
	s_waitcnt vmcnt(15)
	v_pk_add_f32 v[52:53], v[52:53], v[202:203]
	v_pk_add_f32 v[50:51], v[50:51], v[200:201]
	global_store_dwordx4 v[252:253], v[50:53], off offset:576
	s_waitcnt vmcnt(15)
	v_pk_add_f32 v[48:49], v[48:49], v[206:207]
	v_pk_add_f32 v[46:47], v[46:47], v[204:205]
	global_store_dwordx4 v[140:141], v[46:49], off
	s_waitcnt vmcnt(15)
	v_pk_add_f32 v[44:45], v[44:45], v[210:211]
	v_pk_add_f32 v[42:43], v[42:43], v[208:209]
	global_store_dwordx4 v[140:141], v[42:45], off offset:64
	s_waitcnt vmcnt(15)
	v_pk_add_f32 v[40:41], v[40:41], v[214:215]
	v_pk_add_f32 v[38:39], v[38:39], v[212:213]
	global_store_dwordx4 v[140:141], v[38:41], off offset:512
	s_waitcnt vmcnt(15)
	v_pk_add_f32 v[36:37], v[36:37], v[218:219]
	v_pk_add_f32 v[34:35], v[34:35], v[216:217]
	global_store_dwordx4 v[140:141], v[34:37], off offset:576
	s_waitcnt vmcnt(15)
	v_pk_add_f32 v[32:33], v[32:33], v[222:223]
	v_pk_add_f32 v[30:31], v[30:31], v[220:221]
	global_store_dwordx4 v[142:143], v[30:33], off
	s_waitcnt vmcnt(15)
	v_pk_add_f32 v[28:29], v[28:29], v[226:227]
	v_pk_add_f32 v[26:27], v[26:27], v[224:225]
	global_store_dwordx4 v[142:143], v[26:29], off offset:64
	s_waitcnt vmcnt(15)
	v_pk_add_f32 v[24:25], v[24:25], v[230:231]
	v_pk_add_f32 v[22:23], v[22:23], v[228:229]
	global_store_dwordx4 v[142:143], v[22:25], off offset:512
	s_waitcnt vmcnt(15)
	v_pk_add_f32 v[20:21], v[20:21], v[234:235]
	v_pk_add_f32 v[18:19], v[18:19], v[232:233]
	global_store_dwordx4 v[142:143], v[18:21], off offset:576
	s_waitcnt vmcnt(15)
	v_pk_add_f32 v[16:17], v[16:17], v[238:239]
	v_pk_add_f32 v[14:15], v[14:15], v[236:237]
	global_store_dwordx4 v[196:197], v[14:17], off
	s_waitcnt vmcnt(15)
	v_pk_add_f32 v[12:13], v[12:13], v[242:243]
	v_pk_add_f32 v[10:11], v[10:11], v[240:241]
	global_store_dwordx4 v[196:197], v[10:13], off offset:64
	s_waitcnt vmcnt(15)
	v_pk_add_f32 v[8:9], v[8:9], v[246:247]
	v_pk_add_f32 v[6:7], v[6:7], v[244:245]
	global_store_dwordx4 v[196:197], v[6:9], off offset:512
	s_waitcnt vmcnt(15)
	v_pk_add_f32 v[4:5], v[4:5], v[250:251]
	v_pk_add_f32 v[2:3], v[2:3], v[248:249]
	global_store_dwordx4 v[196:197], v[2:5], off offset:576
	s_mov_b64 s[2:3], -1
	s_andn2_b64 vcc, exec, s[4:5]
	s_cbranch_vccnz .LBB0_876
	s_andn2_b64 vcc, exec, s[6:7]
	s_cbranch_vccnz .LBB0_875
	s_barrier
	s_branch .LBB0_875
